# attention: each wave touches the cache lines of its K/V chunks one tile further ahead (global_load_lds_dword into scratch LDS) behind the regular loads
# baseline (speedup 1.0000x reference)
.LBB0_229:
	s_or_b64 exec, exec, s[0:1]
	s_waitcnt lgkmcnt(0)
	s_barrier
	ds_read_b32 v0, v181
	s_mov_b64 s[0:1], -1
	s_waitcnt lgkmcnt(0)
	v_cmp_lt_i32_e32 vcc, s25, v0
	v_readfirstlane_b32 s4, v0
	s_cbranch_vccnz .LBB0_224
	s_ashr_i32 s0, s4, 31
	s_lshr_b32 s0, s0, 23
	s_add_i32 s0, s4, s0
	s_and_b32 s0, s0, 0xfffffe00
	s_sub_i32 s6, s4, s0
	v_readfirstlane_b32 s0, v183
	s_ashr_i32 s7, s6, 5
	s_lshr_b32 s0, s0, 2
	s_sub_i32 s8, 15, s7
	s_and_b32 s9, s0, 0x3ffffff0
	s_lshl_b32 s0, s6, 8
	s_and_b32 s4, s6, 7
	s_lshl_b32 s5, s8, 7
	s_and_b32 s16, s0, 0x1800
	s_add_i32 s37, s9, s5
	s_add_i32 s10, s4, 1
	s_mul_i32 s0, s16, 0xc000
	s_add_u32 s0, s74, s0
	s_addc_u32 s1, s75, 0
	s_lshl_b32 s36, s4, 8
	s_mul_i32 s11, s8, 0x600000
	s_mul_hi_u32 s5, s5, 0xc000
	s_add_u32 s11, s0, s11
	s_addc_u32 s5, s1, s5
	s_lshl_b32 s4, s4, 9
	s_add_u32 s4, s11, s4
	s_addc_u32 s5, s5, 0
	v_mov_b32_e32 v149, v145
	v_lshl_add_u64 v[0:1], s[4:5], 0, v[148:149]
	v_lshl_add_u64 v[28:29], v[0:1], 0, s[18:19]
	v_mov_b32_e32 v151, v145
	v_lshl_add_u64 v[24:25], v[28:29], 0, v[150:151]
	v_add_co_u32_e32 v8, vcc, s27, v24
	v_mov_b32_e32 v153, v145
	s_nop 0
	v_addc_co_u32_e32 v9, vcc, 0, v25, vcc
	v_add_co_u32_e32 v16, vcc, s28, v24
	v_or_b32_e32 v33, s36, v174
	s_waitcnt lgkmcnt(0)
	s_barrier
	v_lshl_add_u64 v[4:5], v[28:29], 0, v[152:153]
	v_addc_co_u32_e32 v17, vcc, 0, v25, vcc
	global_load_dwordx4 v[0:3], v[24:25], off
	s_nop 0
	global_load_dwordx4 v[4:7], v[4:5], off
	v_add_co_u32_e32 v24, vcc, s29, v24
	v_lshlrev_b32_e32 v162, 1, v33
	v_mov_b32_e32 v163, v145
	v_or_b32_e32 v32, s36, v173
	v_mov_b32_e32 v155, v145
	v_mov_b32_e32 v157, v145
	v_addc_co_u32_e32 v25, vcc, 0, v25, vcc
	v_mov_b32_e32 v159, v145
	v_lshl_add_u64 v[48:49], s[0:1], 0, v[162:163]
	v_lshl_add_u64 v[12:13], v[28:29], 0, v[154:155]
	v_lshl_add_u64 v[20:21], v[28:29], 0, v[156:157]
	v_lshl_add_u64 v[28:29], v[28:29], 0, v[158:159]
	v_lshlrev_b32_e32 v144, 1, v32
	v_add_co_u32_e32 v44, vcc, s30, v48
	global_load_dwordx4 v[8:11], v[8:9], off
	s_nop 0
	global_load_dwordx4 v[12:15], v[12:13], off
	s_nop 0
	global_load_dwordx4 v[16:19], v[16:17], off
	s_nop 0
	global_load_dwordx4 v[20:23], v[20:21], off
	v_addc_co_u32_e32 v45, vcc, 0, v49, vcc
	global_load_dwordx4 v[24:27], v[24:25], off
	v_lshl_add_u64 v[50:51], s[0:1], 0, v[144:145]
	global_load_dwordx4 v[28:31], v[28:29], off
	s_nop 0
	global_load_dwordx4 v[32:35], v144, s[0:1]
	global_load_dwordx4 v[36:39], v144, s[0:1] offset:256
	s_lshl_b32 s38, s8, 2
	v_add_co_u32_e32 v50, vcc, s27, v50
	s_add_i32 s38, s38, 4
	global_load_dwordx4 v[40:43], v162, s[0:1]
	v_addc_co_u32_e32 v51, vcc, 0, v51, vcc
	global_load_dwordx4 v[44:47], v[44:45], off
	s_add_u32 s0, s0, 0x180000
	v_add_co_u32_e32 v48, vcc, s31, v48
	s_addc_u32 s1, s1, 0
	s_nop 0
	v_addc_co_u32_e32 v49, vcc, 0, v49, vcc
	global_load_dwordx4 v[116:119], v[50:51], off offset:256
	global_load_dwordx4 v[132:135], v[48:49], off
	global_load_dwordx4 v[124:127], v144, s[0:1]
	global_load_dwordx4 v[140:143], v162, s[0:1]
	s_add_u32 s14, s0, 0x180000
	s_addc_u32 s15, s1, 0
	s_mov_b32 m0, 0x27100
	s_nop 0
	global_load_lds_dword v144, s[14:15]
	global_load_lds_dword v144, s[14:15] offset:256
	global_load_lds_dword v162, s[14:15]
	s_add_u32 s14, s14, 0xc0000
	s_addc_u32 s15, s15, 0
	global_load_lds_dword v162, s[14:15]
	v_cvt_f32_ubyte0_e32 v48, s10
	s_bfe_u32 s0, s6, 0x20003
	v_exp_f32_e64 v48, -v48
	s_or_b32 s41, s37, 15
	s_mul_i32 s0, s0, 0x6000000
	s_add_u32 s22, s70, s0
	s_addc_u32 s23, s71, 0
	s_lshl_b32 s0, s7, 2
	s_sub_i32 s42, s0, 64
	s_lshl_b32 s0, s7, 7
	v_mul_f32_e32 v149, 0x3fb8aa3b, v48
	s_mov_b32 s39, 31
	s_mov_b32 s40, 2
	v_mul_f32_e32 v151, 0x41800000, v149
	s_waitcnt vmcnt(19)
	ds_write_b128 v184, v[0:3]
	s_waitcnt vmcnt(18)
	ds_write_b128 v185, v[4:7]
	s_waitcnt vmcnt(17)
	ds_write_b128 v184, v[8:11] offset:8704
	s_waitcnt vmcnt(16)
	ds_write_b128 v186, v[12:15]
	s_waitcnt vmcnt(15)
	ds_write_b128 v184, v[16:19] offset:17408
	s_waitcnt vmcnt(14)
	ds_write_b128 v187, v[20:23]
	s_waitcnt vmcnt(13)
	ds_write_b128 v184, v[24:27] offset:26112
	s_waitcnt vmcnt(12)
	ds_write_b128 v188, v[28:31]
	s_waitcnt vmcnt(11)
	ds_write_b128 v189, v[32:35]
	s_waitcnt vmcnt(10)
	ds_write_b128 v189, v[36:39] offset:8704
	s_waitcnt vmcnt(9)
	ds_write_b128 v190, v[40:43] offset:17408
	s_waitcnt vmcnt(8)
	ds_write_b128 v190, v[44:47] offset:26112
	v_or_b32_e32 v0, s9, v169
	s_waitcnt lgkmcnt(0)
	s_barrier
	v_mul_lo_u32 v0, v0, s3
	v_add_u32_e32 v1, s9, v180
	v_mov_b32_e32 v40, v145
	v_mov_b32_e32 v41, v145
	v_mov_b32_e32 v42, v145
	v_mov_b32_e32 v43, v145
	v_subrev_u32_e32 v194, s0, v1
	v_add_u32_e32 v195, v177, v0
	v_mov_b64_e32 v[58:59], v[42:43]
	v_mov_b64_e32 v[66:67], v[42:43]
	v_mov_b64_e32 v[74:75], v[42:43]
	v_mov_b64_e32 v[82:83], v[42:43]
	v_mov_b64_e32 v[90:91], v[42:43]
	v_mov_b64_e32 v[98:99], v[42:43]
	v_mov_b64_e32 v[106:107], v[42:43]
	v_mov_b64_e32 v[114:115], v[42:43]
	v_mov_b64_e32 v[130:131], v[42:43]
	v_mov_b64_e32 v[0:1], v[40:41]
	v_mov_b64_e32 v[4:5], v[40:41]
	v_mov_b64_e32 v[8:9], v[40:41]
	v_mov_b64_e32 v[16:17], v[40:41]
	v_mov_b64_e32 v[28:29], v[40:41]
	v_mov_b64_e32 v[46:47], v[42:43]
	v_mov_b64_e32 v[50:51], v[42:43]
	v_mov_b64_e32 v[62:63], v[42:43]
	v_mov_b64_e32 v[70:71], v[42:43]
	v_mov_b64_e32 v[78:79], v[42:43]
	v_mov_b64_e32 v[86:87], v[42:43]
	v_mov_b64_e32 v[94:95], v[42:43]
	v_mov_b64_e32 v[102:103], v[42:43]
	v_mov_b64_e32 v[110:111], v[42:43]
	v_mov_b64_e32 v[122:123], v[42:43]
	v_mov_b64_e32 v[138:139], v[42:43]
	v_mov_b64_e32 v[54:55], v[42:43]
	v_mov_b64_e32 v[36:37], v[40:41]
	v_mov_b64_e32 v[32:33], v[40:41]
	v_mov_b64_e32 v[24:25], v[40:41]
	v_mov_b64_e32 v[20:21], v[40:41]
	v_mov_b64_e32 v[12:13], v[40:41]
	v_mul_f32_e32 v153, 0, v149
	v_add_f32_e32 v155, v149, v149
	v_mul_f32_e32 v157, 0x40400000, v149
	v_mul_f32_e32 v159, 0x41880000, v149
	v_mul_f32_e32 v161, 0x41900000, v149
	v_mul_f32_e32 v193, 0x41980000, v149
	v_mov_b32_e32 v164, v145
	v_mov_b32_e32 v165, v145
	v_mov_b32_e32 v166, 0xf149f2ca
	v_mov_b64_e32 v[56:57], v[40:41]
	v_mov_b64_e32 v[64:65], v[40:41]
	v_mov_b64_e32 v[72:73], v[40:41]
	v_mov_b64_e32 v[80:81], v[40:41]
	v_mov_b64_e32 v[88:89], v[40:41]
	v_mov_b64_e32 v[96:97], v[40:41]
	v_mov_b64_e32 v[104:105], v[40:41]
	v_mov_b64_e32 v[112:113], v[40:41]
	v_mov_b64_e32 v[128:129], v[40:41]
	v_mov_b64_e32 v[2:3], v[42:43]
	v_mov_b64_e32 v[6:7], v[42:43]
	v_mov_b64_e32 v[10:11], v[42:43]
	v_mov_b64_e32 v[18:19], v[42:43]
	v_mov_b64_e32 v[30:31], v[42:43]
	v_mov_b64_e32 v[44:45], v[40:41]
	v_mov_b64_e32 v[48:49], v[40:41]
	v_mov_b64_e32 v[60:61], v[40:41]
	v_mov_b64_e32 v[68:69], v[40:41]
	v_mov_b64_e32 v[76:77], v[40:41]
	v_mov_b64_e32 v[84:85], v[40:41]
	v_mov_b64_e32 v[92:93], v[40:41]
	v_mov_b64_e32 v[100:101], v[40:41]
	v_mov_b64_e32 v[108:109], v[40:41]
	v_mov_b64_e32 v[120:121], v[40:41]
	v_mov_b64_e32 v[136:137], v[40:41]
	v_mov_b32_e32 v167, 0xf149f2ca
	v_mov_b64_e32 v[52:53], v[40:41]
	v_mov_b64_e32 v[38:39], v[42:43]
	v_mov_b64_e32 v[34:35], v[42:43]
	v_mov_b64_e32 v[26:27], v[42:43]
	v_mov_b64_e32 v[22:23], v[42:43]
	v_mov_b64_e32 v[14:15], v[42:43]
	v_readfirstlane_b32 s5, v149
	v_readfirstlane_b32 s6, v155
	v_readfirstlane_b32 s7, v157
	v_readfirstlane_b32 s8, v151
	v_readfirstlane_b32 s9, v159
	v_readfirstlane_b32 s10, v161
	v_readfirstlane_b32 s11, v193
	s_mov_b32 s4, 0
	s_mov_b32 s12, 0x3e0293ee
	s_mov_b32 s13, 0x3e0293ee
	v_readfirstlane_b32 s86, v149
	v_readfirstlane_b32 s87, v151
	v_readfirstlane_b32 s88, v155
	v_readfirstlane_b32 s89, v157
	v_readfirstlane_b32 s90, v159
	ds_read_b128 v[240:243], v195
	ds_read_b128 v[244:247], v195 offset:64
	ds_read_b128 v[248:251], v195 offset:128
	ds_read_b128 v[252:255], v195 offset:192
	ds_read_b128 v[148:151], v195 offset:34816
	ds_read_b128 v[152:155], v195 offset:34880
	ds_read_b128 v[156:159], v195 offset:34944
	ds_read_b128 v[184:187], v195 offset:35008
	s_waitcnt lgkmcnt(0)
.LBB0_231:
	s_bitcmp1_b32 s40, 0
	s_cselect_b32 s43, 0x8800, 0
	s_cmp_lt_u32 s97, 4
	s_cbranch_scc1 .Latt_top_done
	s_add_i32 s0, s40, -1
	s_cmp_ge_u32 s0, s38
	s_cbranch_scc1 .Latt_top_done
	s_sub_i32 s0, 0, s43
	v_add_u32_e32 v238, s0, v175
	s_cmp_ge_u32 s40, s38
	s_cbranch_scc1 .Latt_st_lastT
	s_waitcnt vmcnt(5)
	ds_write_b128 v238, v[124:127] offset:34816
	ds_write_b128 v238, v[116:119] offset:43520
	v_add_u32_e32 v238, s0, v176
	s_waitcnt vmcnt(4)
	ds_write_b128 v238, v[140:143] offset:52224
	ds_write_b128 v238, v[132:135] offset:60928
	v_lshl_add_u64 v[116:117], s[22:23], 0, v[144:145]
	v_add_co_u32_e32 v116, vcc, 0x14400000, v116
	v_lshl_add_u64 v[132:133], s[22:23], 0, v[162:163]
	s_nop 0
	v_addc_co_u32_e32 v117, vcc, 0, v117, vcc
	v_add_co_u32_e32 v134, vcc, 0x14400000, v132
	global_load_dwordx4 v[124:127], v[116:117], off
	s_nop 0
	global_load_dwordx4 v[116:119], v[116:117], off offset:256
	v_addc_co_u32_e32 v135, vcc, 0, v133, vcc
	v_add_co_u32_e32 v132, vcc, 0x144c0000, v132
	s_nop 1
	v_addc_co_u32_e32 v133, vcc, 0, v133, vcc
	global_load_dwordx4 v[140:143], v[134:135], off
	s_nop 0
	global_load_dwordx4 v[132:135], v[132:133], off
	s_add_i32 s0, s40, 1
	s_cmp_lt_u32 s0, s38
	s_cselect_b32 s0, 0x180000, 0
	s_add_u32 s14, s22, s0
	s_addc_u32 s15, s23, 0
	s_add_u32 s14, s14, 0x14400000
	s_addc_u32 s15, s15, 0
	s_mov_b32 m0, 0x27100
	s_nop 0
	global_load_lds_dword v144, s[14:15]
	global_load_lds_dword v144, s[14:15] offset:256
	global_load_lds_dword v162, s[14:15]
	s_add_u32 s14, s14, 0xc0000
	s_addc_u32 s15, s15, 0
	global_load_lds_dword v162, s[14:15]
	s_branch .Latt_top_done
.Latt_st_lastT:
	s_waitcnt vmcnt(1)
	ds_write_b128 v238, v[124:127] offset:34816
	ds_write_b128 v238, v[116:119] offset:43520
	v_add_u32_e32 v238, s0, v176
	s_waitcnt vmcnt(0)
	ds_write_b128 v238, v[140:143] offset:52224
	ds_write_b128 v238, v[132:135] offset:60928

.LBB0_236:
	s_cmp_ge_u32 s97, 4
	s_cbranch_scc1 .LBB0_238
	s_sub_i32 s0, 0, s43
	v_add_u32_e32 v166, s0, v175
	s_cmp_ge_u32 s40, s38
	s_cbranch_scc1 .Latt_st_lastB
	s_waitcnt vmcnt(5)
	ds_write_b128 v166, v[124:127] offset:34816
	ds_write_b128 v166, v[116:119] offset:43520
	v_add_u32_e32 v166, s0, v176
	s_waitcnt vmcnt(4)
	ds_write_b128 v166, v[140:143] offset:52224
	ds_write_b128 v166, v[132:135] offset:60928
	v_lshl_add_u64 v[116:117], s[22:23], 0, v[144:145]
	v_add_co_u32_e32 v116, vcc, 0x14400000, v116
	v_lshl_add_u64 v[132:133], s[22:23], 0, v[162:163]
	s_nop 0
	v_addc_co_u32_e32 v117, vcc, 0, v117, vcc
	v_add_co_u32_e32 v134, vcc, 0x14400000, v132
	global_load_dwordx4 v[124:127], v[116:117], off
	s_nop 0
	global_load_dwordx4 v[116:119], v[116:117], off offset:256
	v_addc_co_u32_e32 v135, vcc, 0, v133, vcc
	v_add_co_u32_e32 v132, vcc, 0x144c0000, v132
	s_nop 1
	v_addc_co_u32_e32 v133, vcc, 0, v133, vcc
	global_load_dwordx4 v[140:143], v[134:135], off
	s_nop 0
	global_load_dwordx4 v[132:135], v[132:133], off
	s_add_i32 s0, s40, 1
	s_cmp_lt_u32 s0, s38
	s_cselect_b32 s0, 0x180000, 0
	s_add_u32 s14, s22, s0
	s_addc_u32 s15, s23, 0
	s_add_u32 s14, s14, 0x14400000
	s_addc_u32 s15, s15, 0
	s_mov_b32 m0, 0x27100
	s_nop 0
	global_load_lds_dword v144, s[14:15]
	global_load_lds_dword v144, s[14:15] offset:256
	global_load_lds_dword v162, s[14:15]
	s_add_u32 s14, s14, 0xc0000
	s_addc_u32 s15, s15, 0
	global_load_lds_dword v162, s[14:15]
	s_branch .LBB0_238
.Latt_st_lastB:
	s_waitcnt vmcnt(1)
	ds_write_b128 v166, v[124:127] offset:34816
	ds_write_b128 v166, v[116:119] offset:43520
	v_add_u32_e32 v166, s0, v176
	s_waitcnt vmcnt(0)
	ds_write_b128 v166, v[140:143] offset:52224
	ds_write_b128 v166, v[132:135] offset:60928

	.amdhsa_kernel _Z8mega_fwd4Args
		.amdhsa_group_segment_fixed_size 20736
		.amdhsa_private_segment_fixed_size 0
		.amdhsa_kernarg_size 392
		.amdhsa_user_sgpr_count 2
		.amdhsa_user_sgpr_dispatch_ptr 0
		.amdhsa_user_sgpr_queue_ptr 0
		.amdhsa_user_sgpr_kernarg_segment_ptr 1
		.amdhsa_user_sgpr_dispatch_id 0
		.amdhsa_user_sgpr_kernarg_preload_length 0
		.amdhsa_user_sgpr_kernarg_preload_offset 0
		.amdhsa_user_sgpr_private_segment_size 0
		.amdhsa_uses_dynamic_stack 0
		.amdhsa_enable_private_segment 0
		.amdhsa_system_sgpr_workgroup_id_x 1
		.amdhsa_system_sgpr_workgroup_id_y 0
		.amdhsa_system_sgpr_workgroup_id_z 0
		.amdhsa_system_sgpr_workgroup_info 0
		.amdhsa_system_vgpr_workitem_id 2
		.amdhsa_next_free_vgpr 256
		.amdhsa_next_free_sgpr 100
		.amdhsa_accum_offset 256
		.amdhsa_reserve_vcc 1
		.amdhsa_float_round_mode_32 0
		.amdhsa_float_round_mode_16_64 0
		.amdhsa_float_denorm_mode_32 3
		.amdhsa_float_denorm_mode_16_64 3
		.amdhsa_dx10_clamp 1
		.amdhsa_ieee_mode 1
		.amdhsa_fp16_overflow 0
		.amdhsa_tg_split 0
		.amdhsa_exception_fp_ieee_invalid_op 0
		.amdhsa_exception_fp_denorm_src 0
		.amdhsa_exception_fp_ieee_div_zero 0
		.amdhsa_exception_fp_ieee_overflow 0
		.amdhsa_exception_fp_ieee_underflow 0
		.amdhsa_exception_fp_ieee_inexact 0
		.amdhsa_exception_int_div_zero 0
	.end_amdhsa_kernel

amdhsa.kernels:
  - .agpr_count:     0
    .args:
      - .offset:         0
        .size:           136
        .value_kind:     by_value
      - .offset:         136
        .size:           4
        .value_kind:     hidden_block_count_x
      - .offset:         140
        .size:           4
        .value_kind:     hidden_block_count_y
      - .offset:         144
        .size:           4
        .value_kind:     hidden_block_count_z
      - .offset:         148
        .size:           2
        .value_kind:     hidden_group_size_x
      - .offset:         150
        .size:           2
        .value_kind:     hidden_group_size_y
      - .offset:         152
        .size:           2
        .value_kind:     hidden_group_size_z
      - .offset:         154
        .size:           2
        .value_kind:     hidden_remainder_x
      - .offset:         156
        .size:           2
        .value_kind:     hidden_remainder_y
      - .offset:         158
        .size:           2
        .value_kind:     hidden_remainder_z
      - .offset:         176
        .size:           8
        .value_kind:     hidden_global_offset_x
      - .offset:         184
        .size:           8
        .value_kind:     hidden_global_offset_y
      - .offset:         192
        .size:           8
        .value_kind:     hidden_global_offset_z
      - .offset:         200
        .size:           2
        .value_kind:     hidden_grid_dims
      - .offset:         224
        .size:           8
        .value_kind:     hidden_multigrid_sync_arg
      - .offset:         256
        .size:           4
        .value_kind:     hidden_dynamic_lds_size
    .group_segment_fixed_size: 20736
    .kernarg_segment_align: 8
    .kernarg_segment_size: 392
    .language:       OpenCL C
    .language_version:
      - 2
      - 0
    .max_flat_workgroup_size: 512
    .name:           _Z8mega_fwd4Args
    .private_segment_fixed_size: 0
    .sgpr_count:     106
    .sgpr_spill_count: 31
    .symbol:         _Z8mega_fwd4Args.kd
    .uniform_work_group_size: 1
    .uses_dynamic_stack: false
    .vgpr_count:     256
    .vgpr_spill_count: 0
    .wavefront_size: 64
